# attention key loop: 4 compiler lgkmcnt(0) drains replaced by counted lgkmcnt waits at each fragment's first consumer
# speedup vs baseline: 1.0073x; 1.0073x over previous
.LBB0_1326:
	s_mul_hi_u32 s34, s77, 0xaaaaaaab
	s_lshr_b32 s34, s34, 1
	s_mul_i32 s34, s34, 0xc000
	v_subrev_u32_e32 v0, s34, v130
	s_add_i32 s34, s2, s36
	v_add_u32_e32 v0, s34, v0
	ds_read_b128 v[66:69], v0
	ds_read_b128 v[82:85], v0 offset:4096
	ds_read_b128 v[94:97], v0 offset:6144
	ds_read_b128 v[98:101], v0 offset:1024
	ds_read_b128 v[86:89], v0 offset:2048
	ds_read_b128 v[132:135], v0 offset:3072
	v_xor_b32_e32 v62, 0x80000000, v113
	v_mov_b32_e32 v63, v62
	v_mov_b32_e32 v64, v62
	v_mov_b32_e32 v65, v62
	s_lshl_b32 s34, s49, 14
	v_add_u32_e32 v131, s34, v124
	s_waitcnt lgkmcnt(5)
	v_mfma_f32_16x16x32_bf16 v[66:69], v[66:69], v[10:13], v[62:65]
	ds_read_b128 v[78:81], v0 offset:5120
	s_waitcnt lgkmcnt(2)
	v_mfma_f32_16x16x32_bf16 v[136:139], v[86:89], v[10:13], v[62:65]
	v_max_f32_e32 v86, v77, v77
	v_max_f32_e32 v87, v76, v76
	v_max_f32_e32 v86, v87, v86
	v_max3_f32 v102, v74, v75, v86
	v_max_f32_e32 v86, v73, v73
	v_max_f32_e32 v87, v72, v72
	v_max_f32_e32 v86, v87, v86
	v_max3_f32 v103, v70, v71, v86
	ds_read_b128 v[86:89], v0 offset:7168
	v_mfma_f32_16x16x32_bf16 v[90:93], v[82:85], v[10:13], v[62:65]
	v_mfma_f32_16x16x32_bf16 v[94:97], v[94:97], v[10:13], v[62:65]
	v_max_f32_e32 v0, v23, v23
	ds_read_b128 v[82:85], v131 offset:49152
	s_nop 0
	v_max_f32_e32 v62, v22, v22
	v_max_f32_e32 v0, v62, v0
	v_max_f32_e32 v62, v25, v25
	v_max_f32_e32 v63, v24, v24
	v_max_f32_e32 v62, v63, v62
	v_max_f32_e32 v63, v29, v29
	v_max_f32_e32 v64, v28, v28
	v_max_f32_e32 v63, v64, v63
	v_max3_f32 v63, v26, v27, v63
	v_max3_f32 v0, v0, v62, v63
	v_max3_f32 v0, v102, v103, v0
	ds_read_b128 v[102:105], v131 offset:51200
	v_mfma_f32_16x16x32_bf16 v[62:65], v[98:101], v[18:21], v[66:69]
	s_waitcnt lgkmcnt(4)
	v_mfma_f32_16x16x32_bf16 v[66:69], v[132:135], v[18:21], v[136:139]
	v_mov_b32_e32 v132, v0
	s_nop 1
	v_permlane16_swap_b32_e32 v0, v132
	v_max_f32_e32 v132, v132, v132
	v_max_f32_e32 v0, v0, v0
	v_max_f32_e32 v0, v0, v132
	v_mov_b32_e32 v132, v0
	s_nop 1
	v_permlane32_swap_b32_e32 v0, v132
	ds_read_b128 v[98:101], v131 offset:53248
	v_max_f32_e32 v132, v132, v132
	v_max_f32_e32 v0, v0, v0
	v_max_f32_e32 v0, v0, v132
	s_mov_b32 s34, 0x41000000
	v_cmp_lt_f32_e32 vcc, s34, v0
	s_cmp_lg_u64 vcc, 0
	s_cselect_b64 s[34:35], -1, 0
	s_cbranch_vccz .LBB0_1328
	v_cndmask_b32_e32 v132, 0, v0, vcc
	v_exp_f32_e64 v0, -v132
	v_sub_f32_e32 v74, v74, v132
	v_sub_f32_e32 v75, v75, v132
	v_sub_f32_e32 v76, v76, v132
	v_sub_f32_e32 v77, v77, v132
	v_sub_f32_e32 v70, v70, v132
	v_sub_f32_e32 v71, v71, v132
	v_sub_f32_e32 v72, v72, v132
	v_sub_f32_e32 v73, v73, v132
	v_sub_f32_e32 v22, v22, v132
	v_sub_f32_e32 v23, v23, v132
	v_sub_f32_e32 v24, v24, v132
	v_sub_f32_e32 v25, v25, v132
	v_sub_f32_e32 v26, v26, v132
	v_sub_f32_e32 v27, v27, v132
	v_sub_f32_e32 v28, v28, v132
	v_sub_f32_e32 v29, v29, v132
	v_add_f32_e32 v113, v113, v132
	s_branch .LBB0_1329

.LBB0_1329:
	v_mov_b32_e32 v133, v22
	v_mov_b32_e32 v138, v23
	v_mov_b32_e32 v139, v24
	v_mov_b32_e32 v140, v25
	v_mov_b32_e32 v141, v26
	v_mov_b32_e32 v142, v27
	v_mov_b32_e32 v143, v28
	v_mov_b32_e32 v144, v29
	ds_read_b128 v[134:137], v131 offset:55296
	s_waitcnt lgkmcnt(5)
	v_mfma_f32_16x16x32_bf16 v[22:25], v[78:81], v[18:21], v[90:93]
	ds_read_b128 v[78:81], v131 offset:57344
	s_waitcnt lgkmcnt(5)
	v_mfma_f32_16x16x32_bf16 v[26:29], v[86:89], v[18:21], v[94:97]
	ds_read_b128 v[86:89], v131 offset:59392
	s_waitcnt lgkmcnt(5)
	v_mfma_f32_16x16x32_bf16 v[30:33], v[82:85], v[14:17], v[30:33]
	v_exp_f32_e32 v145, v74
	v_exp_f32_e32 v146, v75
	v_exp_f32_e32 v147, v76
	v_exp_f32_e32 v148, v77
	ds_read_b128 v[74:77], v131 offset:61440
	s_waitcnt lgkmcnt(5)
	v_mfma_f32_16x16x32_bf16 v[50:53], v[102:105], v[14:17], v[50:53]
	ds_read_b128 v[82:85], v131 offset:63488
	s_waitcnt lgkmcnt(5)
	v_mfma_f32_16x16x32_bf16 v[42:45], v[98:101], v[14:17], v[42:45]
	ds_read_b128 v[90:93], v131 offset:50176
	s_waitcnt lgkmcnt(5)
	v_mfma_f32_16x16x32_bf16 v[34:37], v[134:137], v[14:17], v[34:37]
	v_exp_f32_e32 v98, v70
	v_exp_f32_e32 v99, v71
	v_exp_f32_e32 v100, v72
	v_exp_f32_e32 v101, v73
	ds_read_b128 v[70:73], v131 offset:52224
	s_waitcnt lgkmcnt(5)
	v_mfma_f32_16x16x32_bf16 v[58:61], v[78:81], v[14:17], v[58:61]
	ds_read_b128 v[78:81], v131 offset:54272
	s_waitcnt lgkmcnt(5)
	v_mfma_f32_16x16x32_bf16 v[54:57], v[86:89], v[14:17], v[54:57]
	ds_read_b128 v[86:89], v131 offset:56320
	s_waitcnt lgkmcnt(5)
	v_mfma_f32_16x16x32_bf16 v[46:49], v[74:77], v[14:17], v[46:49]
	v_exp_f32_e32 v102, v133
	v_exp_f32_e32 v103, v138
	v_exp_f32_e32 v104, v139
	v_exp_f32_e32 v105, v140
	ds_read_b128 v[74:77], v131 offset:58368
	s_waitcnt lgkmcnt(5)
	v_mfma_f32_16x16x32_bf16 v[38:41], v[82:85], v[14:17], v[38:41]
	s_mov_b32 s50, s48
	s_mov_b32 s51, s48
	s_mov_b32 s49, s48
	v_mov_b64_e32 v[84:85], s[50:51]
	v_mov_b64_e32 v[82:83], s[48:49]
	s_nop 1
	v_mfma_f32_16x16x32_bf16 v[2:5], v[82:85], v[14:17], v[2:5]
	ds_read_b128 v[94:97], v131 offset:60416
	s_waitcnt lgkmcnt(5)
	v_mfma_f32_16x16x32_bf16 v[30:33], v[90:93], v[6:9], v[30:33]
	v_exp_f32_e32 v133, v141
	v_exp_f32_e32 v134, v142
	v_exp_f32_e32 v135, v143
	v_exp_f32_e32 v136, v144
	ds_read_b128 v[90:93], v131 offset:62464
	s_waitcnt lgkmcnt(5)
	v_mfma_f32_16x16x32_bf16 v[50:53], v[70:73], v[6:9], v[50:53]
	ds_read_b128 v[70:73], v131 offset:64512
	s_waitcnt lgkmcnt(5)
	v_mfma_f32_16x16x32_bf16 v[42:45], v[78:81], v[6:9], v[42:45]
	s_waitcnt lgkmcnt(4)
	v_mfma_f32_16x16x32_bf16 v[34:37], v[86:89], v[6:9], v[34:37]
	v_cvt_pk_bf16_f32 v14, v145, v146
	v_cvt_pk_bf16_f32 v15, v147, v148
	v_cvt_pk_bf16_f32 v16, v98, v99
	v_cvt_pk_bf16_f32 v17, v100, v101
	v_cvt_pk_bf16_f32 v78, v102, v103
	v_cvt_pk_bf16_f32 v79, v104, v105
	v_cvt_pk_bf16_f32 v80, v133, v134
	v_cvt_pk_bf16_f32 v81, v135, v136
	s_waitcnt lgkmcnt(3)
	v_mfma_f32_16x16x32_bf16 v[58:61], v[74:77], v[6:9], v[58:61]
	s_waitcnt lgkmcnt(2)
	v_mfma_f32_16x16x32_bf16 v[54:57], v[94:97], v[6:9], v[54:57]
	s_waitcnt lgkmcnt(1)
	v_mfma_f32_16x16x32_bf16 v[46:49], v[90:93], v[6:9], v[46:49]
	s_waitcnt lgkmcnt(0)
	v_mfma_f32_16x16x32_bf16 v[38:41], v[70:73], v[6:9], v[38:41]
	v_mfma_f32_16x16x32_bf16 v[2:5], v[82:85], v[6:9], v[2:5]
	v_mov_b64_e32 v[6:7], v[78:79]
	v_mov_b64_e32 v[8:9], v[80:81]
	s_andn2_b64 vcc, exec, s[34:35]
	s_cbranch_vccnz .LBB0_1331
	v_sub_f32_e32 v65, v65, v132
	v_sub_f32_e32 v64, v64, v132
	v_sub_f32_e32 v63, v63, v132
	v_sub_f32_e32 v62, v62, v132
	v_sub_f32_e32 v69, v69, v132
	v_sub_f32_e32 v68, v68, v132
	v_sub_f32_e32 v67, v67, v132
	v_sub_f32_e32 v66, v66, v132
	v_sub_f32_e32 v25, v25, v132
	v_sub_f32_e32 v24, v24, v132
	v_sub_f32_e32 v23, v23, v132
	v_sub_f32_e32 v22, v22, v132
	v_sub_f32_e32 v29, v29, v132
	v_sub_f32_e32 v28, v28, v132
	v_sub_f32_e32 v27, v27, v132
	v_sub_f32_e32 v26, v26, v132
	v_pk_mul_f32 v[40:41], v[0:1], v[40:41] op_sel_hi:[0,1]
	v_pk_mul_f32 v[48:49], v[0:1], v[48:49] op_sel_hi:[0,1]
	v_pk_mul_f32 v[56:57], v[0:1], v[56:57] op_sel_hi:[0,1]
	v_pk_mul_f32 v[60:61], v[0:1], v[60:61] op_sel_hi:[0,1]
	v_pk_mul_f32 v[36:37], v[0:1], v[36:37] op_sel_hi:[0,1]
	v_pk_mul_f32 v[44:45], v[0:1], v[44:45] op_sel_hi:[0,1]
	v_pk_mul_f32 v[52:53], v[0:1], v[52:53] op_sel_hi:[0,1]
	v_pk_mul_f32 v[32:33], v[0:1], v[32:33] op_sel_hi:[0,1]
	v_pk_mul_f32 v[38:39], v[0:1], v[38:39] op_sel_hi:[0,1]
	v_pk_mul_f32 v[46:47], v[0:1], v[46:47] op_sel_hi:[0,1]
	v_pk_mul_f32 v[54:55], v[0:1], v[54:55] op_sel_hi:[0,1]
	v_pk_mul_f32 v[58:59], v[0:1], v[58:59] op_sel_hi:[0,1]
	v_pk_mul_f32 v[34:35], v[0:1], v[34:35] op_sel_hi:[0,1]
	v_pk_mul_f32 v[42:43], v[0:1], v[42:43] op_sel_hi:[0,1]
	v_pk_mul_f32 v[50:51], v[0:1], v[50:51] op_sel_hi:[0,1]
	v_pk_mul_f32 v[30:31], v[0:1], v[30:31] op_sel_hi:[0,1]
	v_pk_mul_f32 v[4:5], v[0:1], v[4:5] op_sel_hi:[0,1]
	v_pk_mul_f32 v[2:3], v[0:1], v[2:3] op_sel_hi:[0,1]
